# grid barrier: XCD leader posts its top-level arrival without waiting; every workgroup polls the top-level arrival count; generation kept in LDS (no divisions, no second-level generation words)
# speedup vs baseline: 1.0013x; 1.0013x over previous
; __device__ __forceinline__ unsigned xb_ld(unsigned* p)              { return __hip_atomic_load(p, __ATOMIC_RELAXED, __HIP_MEMORY_SCOPE_AGENT); }
; __device__ __forceinline__ unsigned xb_add(unsigned* p, unsigned v) { return __hip_atomic_fetch_add(p, v, __ATOMIC_RELAXED, __HIP_MEMORY_SCOPE_AGENT); }
; #define XB_SPIN(cond, bar) do { unsigned _sp = 0; while (cond) { __builtin_amdgcn_s_sleep(1); \
;     if ((++_sp & 255u) == 0u) { if (xb_ld(&(bar)[XB_TMO])) break; if (_sp > XB_SPIN_CAP) { atomicAdd(&(bar)[XB_TMO], 1u); break; } } } } while (0)
; __device__ __forceinline__ void xcd_barrier(const XcdBarrier& b) {
;     asm volatile("s_waitcnt vmcnt(0)" ::: "memory");
;     __syncthreads();
;     if (threadIdx.x == 0) {
;         unsigned* bar = b.bar;
;         __builtin_amdgcn_s_waitcnt(0);
;         unsigned nloc = b.st[0], nx = b.st[1];
;         if (nloc == 0u) { xcd_barrier_complete(bar, b.x, nloc, nx); b.st[0] = nloc; b.st[1] = nx; }
;         const unsigned old = xb_add(&bar[XB_XSUB(b.x)], 1u);
;         const unsigned gen = old / nloc;
;         if (old + 1u == (gen + 1u) * nloc) {
;             __builtin_amdgcn_fence(__ATOMIC_RELEASE, "agent");
;             asm volatile("s_waitcnt vmcnt(0)" ::: "memory");
;             const unsigned og = xb_add(&bar[XB_TOP], 1u);
;             const unsigned tg = og / nx;
;             if (og + 1u == (tg + 1u) * nx) xb_add(&bar[XB_TOPGEN], 1u);
;             else XB_SPIN(xb_ld(&bar[XB_TOPGEN]) == tg, bar);
;             __builtin_amdgcn_fence(__ATOMIC_ACQUIRE, "agent");
;             xb_add(&bar[XB_XGEN(b.x)], 1u);
;             asm volatile("s_waitcnt vmcnt(0)" ::: "memory");
;         } else {
;             XB_SPIN(xb_ld(&bar[XB_XGEN(b.x)]) == gen, bar);
;             __builtin_amdgcn_fence(__ATOMIC_ACQUIRE, "agent");
;             asm volatile("s_waitcnt vmcnt(0)" ::: "memory");
;         }
;     }
;     __syncthreads();
; }
.LBB0_115:
	s_waitcnt lgkmcnt(0)
	v_readfirstlane_b32 s10, v2
	v_readfirstlane_b32 s11, v0
	s_lshl_b32 s3, s33, 8
	s_add_u32 s8, s82, s3
	s_addc_u32 s9, s83, 0
	s_add_i32 s3, 0, 0x23ff8
	v_mov_b32_e32 v5, s3
	ds_read_b32 v1, v5
	v_mov_b32_e32 v3, 0x1000
	v_mov_b32_e32 v4, 1
	global_atomic_add v3, v3, v4, s[8:9] offset:1024 sc0
	s_waitcnt vmcnt(0) lgkmcnt(0)
	v_readfirstlane_b32 s12, v3
	v_readfirstlane_b32 s13, v1
	s_add_i32 s13, s13, 1
	v_mov_b32_e32 v1, s13
	ds_write_b32 v5, v1
	s_mul_i32 s14, s13, s10
	s_mul_i32 s15, s13, s11
	s_add_i32 s12, s12, 1
	s_add_u32 s16, s84, 0x1ba7c400
	s_addc_u32 s17, s85, 0
	v_mov_b32_e32 v3, 0
	s_cmp_lg_u32 s12, s14
	s_cbranch_scc1 .Lxb_poll_0
	buffer_wbl2 sc1
	s_waitcnt vmcnt(0)
	global_atomic_add v3, v4, s[16:17]
.Lxb_poll_0:
	s_mov_b32 s18, 0
.Lxb_spin_0:
	global_load_dword v0, v3, s[16:17] sc1
	s_waitcnt vmcnt(0)
	v_readfirstlane_b32 s19, v0
	s_cmp_ge_u32 s19, s15
	s_cbranch_scc1 .Lxb_done_0
	s_sleep 1
	s_add_i32 s18, s18, 1
	s_cmp_lt_u32 s18, 0x8000
	s_cbranch_scc1 .Lxb_spin_0
.Lxb_done_0:
	buffer_inv sc1
	s_waitcnt vmcnt(0) lgkmcnt(0)
